# MLA loop-edge edit: slot-rotation SALU and first K-fragment address adds moved ahead of each step's barrier (on v37)
# speedup vs baseline: 1.0012x; 1.0012x over previous
.LBB0_241:
	s_mov_b32 s79, s70
	s_mov_b32 s70, s0
	s_lshl_b32 s13, s79, 14
	s_lshl_b32 s0, s79, 13
	s_lshl_b32 s1, s70, 14
	s_add_i32 s5, s13, 0
	v_add_u32_e32 v1, s5, v230
	v_add_u32_e32 v102, s5, v232
	s_waitcnt vmcnt(5) lgkmcnt(0)
	s_barrier
	ds_read_b128 v[98:101], v1 offset:49152
	ds_read_b128 v[236:239], v102 offset:57344
	v_add_u32_e32 v1, s5, v231
	v_add_u32_e32 v102, s5, v233
	ds_read_b128 v[240:243], v1 offset:49152
	ds_read_b128 v[244:247], v102 offset:57344
	s_waitcnt lgkmcnt(3)
	v_mfma_f32_32x32x16_bf16 v[114:129], v[98:101], v[130:133], v[66:81]
	v_add_u32_e32 v1, s5, v204
	v_add_u32_e32 v102, v1, v227
	ds_read_b128 v[248:251], v102 offset:49152
	v_add_u32_e32 v190, s1, v202
	v_add_u32_e32 v191, s0, v206
	v_exp_f32_e32 v192, v82
	ds_read_b128 v[210:213], v102 offset:57344
	s_waitcnt lgkmcnt(4)
	v_mfma_f32_32x32x16_bf16 v[98:113], v[236:239], v[130:133], v[66:81]
	v_add_f32_e32 v82, v192, v186
	v_exp_f32_e32 v193, v83
	s_waitcnt lgkmcnt(3)
	v_mfma_f32_32x32x16_bf16 v[114:129], v[240:243], v[134:137], v[114:129]
	v_add_u32_e32 v83, v1, v226
	ds_read_b128 v[186:189], v83 offset:49152
	v_add_f32_e32 v82, v193, v82
	v_exp_f32_e32 v235, v84
	s_waitcnt lgkmcnt(3)
	v_mfma_f32_32x32x16_bf16 v[98:113], v[244:247], v[134:137], v[98:113]
	ds_read_b128 v[236:239], v83 offset:57344
	v_add_f32_e32 v240, v235, v82
	v_exp_f32_e32 v220, v85
	s_waitcnt lgkmcnt(3)
	v_mfma_f32_32x32x16_bf16 v[114:129], v[248:251], v[138:141], v[114:129]
	v_add_u32_e32 v241, v1, v225
	ds_read_b128 v[82:85], v241 offset:49152
	v_exp_f32_e32 v244, v86
	v_add_f32_e32 v86, v220, v240
	s_waitcnt lgkmcnt(3)
	v_mfma_f32_32x32x16_bf16 v[98:113], v[210:213], v[138:141], v[98:113]
	ds_read_b128 v[240:243], v241 offset:57344
	v_add_f32_e32 v86, v244, v86
	v_exp_f32_e32 v245, v87
	s_waitcnt lgkmcnt(3)
	v_mfma_f32_32x32x16_bf16 v[114:129], v[186:189], v[142:145], v[114:129]
	v_add_u32_e32 v87, v1, v224
	ds_read_b128 v[210:213], v87 offset:49152
	v_add_f32_e32 v86, v245, v86
	v_exp_f32_e32 v246, v88
	s_waitcnt lgkmcnt(3)
	v_mfma_f32_32x32x16_bf16 v[98:113], v[236:239], v[142:145], v[98:113]
	ds_read_b128 v[186:189], v87 offset:57344
	v_add_f32_e32 v248, v246, v86
	v_exp_f32_e32 v247, v89
	s_waitcnt lgkmcnt(3)
	v_mfma_f32_32x32x16_bf16 v[114:129], v[82:85], v[154:157], v[114:129]
	v_add_u32_e32 v236, v1, v223
	ds_read_b128 v[86:89], v236 offset:49152
	v_add_f32_e32 v82, v247, v248
	v_exp_f32_e32 v249, v90
	s_waitcnt lgkmcnt(3)
	v_mfma_f32_32x32x16_bf16 v[98:113], v[240:243], v[154:157], v[98:113]
	ds_read_b128 v[236:239], v236 offset:57344
	v_add_f32_e32 v84, v249, v82
	v_exp_f32_e32 v248, v91
	v_cvt_pk_bf16_f32 v82, v192, v193
	v_cvt_pk_bf16_f32 v83, v235, v220
	s_waitcnt lgkmcnt(3)
	v_mfma_f32_32x32x16_bf16 v[114:129], v[210:213], v[150:153], v[114:129]
	v_add_u32_e32 v1, v1, v222
	ds_read_b128 v[240:243], v1 offset:49152
	v_add_f32_e32 v90, v248, v84
	v_exp_f32_e32 v192, v92
	v_cvt_pk_bf16_f32 v84, v244, v245
	v_cvt_pk_bf16_f32 v85, v246, v247
	s_waitcnt lgkmcnt(3)
	v_mfma_f32_32x32x16_bf16 v[98:113], v[186:189], v[150:153], v[98:113]
	ds_read_b128 v[210:213], v1 offset:57344
	v_exp_f32_e32 v1, v93
	v_add_f32_e32 v193, v192, v90
	v_permlane32_swap_b32_e32 v82, v84
	v_permlane32_swap_b32_e32 v83, v85
	s_waitcnt lgkmcnt(3)
	v_mfma_f32_32x32x16_bf16 v[114:129], v[86:89], v[146:149], v[114:129]
	v_add_u32_e32 v186, v191, v221
	ds_read_b128 v[90:93], v186
	v_exp_f32_e32 v220, v94
	v_add_f32_e32 v94, v1, v193
	s_waitcnt lgkmcnt(3)
	v_mfma_f32_32x32x16_bf16 v[98:113], v[236:239], v[146:149], v[98:113]
	ds_read_b128 v[86:89], v186 offset:4096
	v_add_f32_e32 v94, v220, v94
	v_exp_f32_e32 v193, v95
	s_waitcnt lgkmcnt(3)
	v_mfma_f32_32x32x16_bf16 v[114:129], v[240:243], v[158:161], v[114:129]
	v_add_u32_e32 v95, v191, v209
	ds_read_b128 v[186:189], v95
	v_add_f32_e32 v94, v193, v94
	v_exp_f32_e32 v235, v96
	s_waitcnt lgkmcnt(3)
	v_mfma_f32_32x32x16_bf16 v[98:113], v[210:213], v[158:161], v[98:113]
	ds_read_b128 v[236:239], v95 offset:4096
	v_add_f32_e32 v241, v235, v94
	v_exp_f32_e32 v240, v97
	s_waitcnt lgkmcnt(3)
	v_mfma_f32_32x32x16_bf16 v[114:129], v[90:93], v[162:165], v[114:129]
	v_add_u32_e32 v210, v191, v208
	ds_read_b128 v[94:97], v210
	v_add_f32_e32 v241, v240, v241
	s_waitcnt lgkmcnt(3)
	v_mfma_f32_32x32x16_bf16 v[98:113], v[86:89], v[162:165], v[98:113]
	ds_read_b128 v[90:93], v210 offset:4096
	v_cvt_pk_bf16_f32 v86, v249, v248
	v_cvt_pk_bf16_f32 v87, v192, v1
	s_waitcnt lgkmcnt(3)
	v_mfma_f32_32x32x16_bf16 v[114:129], v[186:189], v[166:169], v[114:129]
	v_add_u32_e32 v1, v191, v207
	ds_read_b128 v[210:213], v1
	v_cvt_pk_bf16_f32 v88, v220, v193
	v_cvt_pk_bf16_f32 v89, v235, v240
	s_waitcnt lgkmcnt(3)
	v_mfma_f32_32x32x16_bf16 v[98:113], v[236:239], v[166:169], v[98:113]
	ds_read_b128 v[186:189], v1 offset:4096
	v_permlane32_swap_b32_e32 v86, v88
	v_permlane32_swap_b32_e32 v87, v89
	s_waitcnt lgkmcnt(3)
	v_mfma_f32_32x32x16_bf16 v[114:129], v[94:97], v[170:173], v[114:129]
	v_mov_b32_e32 v1, v241
	s_nop 1
	v_permlane32_swap_b32_e32 v241, v1
	v_add_f32_e32 v1, v241, v1
	v_add_f32_e32 v1, v234, v1
	s_waitcnt lgkmcnt(2)
	v_mfma_f32_32x32x16_bf16 v[98:113], v[90:93], v[170:173], v[98:113]
	ds_read_b64_tr_b16 v[94:95], v190
	ds_read_b64_tr_b16 v[96:97], v190 offset:2048
	s_waitcnt lgkmcnt(3)
	v_mfma_f32_32x32x16_bf16 v[114:129], v[210:213], v[174:177], v[114:129]
	ds_read_b64_tr_b16 v[90:91], v190 offset:512
	ds_read_b64_tr_b16 v[92:93], v190 offset:2560
	s_waitcnt lgkmcnt(4)
	v_mfma_f32_32x32x16_bf16 v[98:113], v[186:189], v[174:177], v[98:113]
	ds_read_b64_tr_b16 v[210:211], v190 offset:1024
	ds_read_b64_tr_b16 v[212:213], v190 offset:3072
	s_add_u32 s18, s30, s46
	s_addc_u32 s19, s31, s47
	s_add_u32 s14, s18, 0x15000000
	s_addc_u32 s15, s19, 0
	s_waitcnt lgkmcnt(4)
	v_mfma_f32_32x32x16_bf16 v[50:65], v[182:185], v[94:97], v[50:65]
	s_add_u32 s6, s18, 0x15018000
	s_addc_u32 s7, s19, 0
	s_add_i32 s5, s1, s76
	s_add_u32 s8, s18, 0x15010100
	ds_read_b64_tr_b16 v[234:235], v190 offset:1536
	ds_read_b64_tr_b16 v[236:237], v190 offset:3584
	s_addc_u32 s9, s19, 0
	s_lshl_b32 s20, s77, 14
	s_add_i32 s12, s20, s73
	s_mov_b32 m0, s12
	s_nop 0
	global_load_lds_dwordx4 v199, s[8:9]
	s_waitcnt lgkmcnt(4)
	v_mfma_f32_32x32x16_bf16 v[34:49], v[182:185], v[90:93], v[34:49]
	ds_read_b64_tr_b16 v[94:95], v190 offset:4096
	ds_read_b64_tr_b16 v[96:97], v190 offset:6144
	s_add_u32 s8, s18, 0x15014100
	s_addc_u32 s9, s19, 0
	s_addk_i32 s12, 0x2000
	s_mov_b32 m0, s12
	s_nop 0
	global_load_lds_dwordx4 v199, s[8:9]
	s_waitcnt lgkmcnt(4)
	v_mfma_f32_32x32x16_bf16 v[18:33], v[182:185], v[210:213], v[18:33]
	ds_read_b64_tr_b16 v[186:187], v190 offset:4608
	ds_read_b64_tr_b16 v[188:189], v190 offset:6656
	s_mov_b32 m0, s5
	s_nop 0
	global_load_lds_dwordx4 v197, s[6:7]
	s_waitcnt lgkmcnt(4)
	v_mfma_f32_32x32x16_bf16 v[2:17], v[182:185], v[234:237], v[2:17]
	ds_read_b64_tr_b16 v[90:91], v190 offset:5120
	ds_read_b64_tr_b16 v[92:93], v190 offset:7168
	s_add_u32 s6, s18, 0x1501a000
	s_addc_u32 s7, s19, 0
	s_addk_i32 s5, 0x1000
	s_mov_b32 m0, s5
	s_nop 0
	global_load_lds_dwordx4 v197, s[6:7]
	v_max_f32_e32 v182, v115, v115
	v_max_f32_e32 v183, v114, v114
	v_max_f32_e32 v182, v183, v182
	v_max3_f32 v183, v116, v117, v99
	v_max3_f32 v182, v182, v98, v100
	v_max3_f32 v182, v182, v101, v118
	v_max3_f32 v183, v183, v120, v121
	v_max3_f32 v182, v182, v119, v102
	v_max3_f32 v183, v183, v104, v105
	v_max3_f32 v182, v182, v103, v122
	v_max3_f32 v183, v183, v124, v125
	v_max3_f32 v182, v182, v123, v106
	v_max3_f32 v183, v183, v108, v109
	v_max3_f32 v182, v182, v107, v126
	v_max3_f32 v183, v183, v128, v129
	v_max3_f32 v182, v182, v127, v110
	v_max3_f32 v183, v183, v112, v113
	v_max3_f32 v182, v182, v111, v183
	v_mov_b32_e32 v183, v182
	s_nop 1
	v_permlane32_swap_b32_e32 v182, v183
	v_max_f32_e32 v183, v183, v183
	v_max_f32_e32 v182, v182, v182
	v_max_f32_e32 v182, v182, v183
	v_cmp_lt_f32_e32 vcc, s92, v182
	s_cmp_lg_u64 vcc, 0
	s_cselect_b64 s[6:7], -1, 0
	s_cbranch_vccnz .LBB0_255

.LBB0_244:
	s_add_i32 s5, s20, 0
	v_add_u32_e32 v83, s5, v230
	v_add_u32_e32 v88, s5, v232
	s_waitcnt vmcnt(5) lgkmcnt(0)
	s_barrier
	ds_read_b128 v[84:87], v83 offset:49152
	ds_read_b128 v[186:189], v88 offset:57344
	v_add_u32_e32 v83, s5, v231
	v_add_u32_e32 v88, s5, v233
	ds_read_b128 v[190:193], v83 offset:49152
	ds_read_b128 v[210:213], v88 offset:57344
	s_waitcnt lgkmcnt(3)
	v_mfma_f32_32x32x16_bf16 v[114:129], v[84:87], v[130:133], v[66:81]
	v_add_u32_e32 v220, s5, v204
	v_add_u32_e32 v83, v220, v227
	ds_read_b128 v[236:239], v83 offset:49152
	v_lshl_add_u32 v234, s77, 13, v206
	v_add_u32_e32 v235, s13, v202
	v_exp_f32_e32 v244, v98
	ds_read_b128 v[240:243], v83 offset:57344
	v_add_f32_e32 v98, v244, v82
	s_waitcnt lgkmcnt(4)
	v_mfma_f32_32x32x16_bf16 v[82:97], v[186:189], v[130:133], v[66:81]
	v_exp_f32_e32 v245, v99
	s_waitcnt lgkmcnt(3)
	v_mfma_f32_32x32x16_bf16 v[114:129], v[190:193], v[134:137], v[114:129]
	v_add_u32_e32 v99, v220, v226
	ds_read_b128 v[186:189], v99 offset:49152
	v_add_f32_e32 v98, v245, v98
	v_exp_f32_e32 v246, v100
	s_waitcnt lgkmcnt(3)
	v_mfma_f32_32x32x16_bf16 v[82:97], v[210:213], v[134:137], v[82:97]
	ds_read_b128 v[190:193], v99 offset:57344
	v_add_f32_e32 v248, v246, v98
	v_exp_f32_e32 v247, v101
	s_waitcnt lgkmcnt(3)
	v_mfma_f32_32x32x16_bf16 v[114:129], v[236:239], v[138:141], v[114:129]
	v_add_u32_e32 v210, v220, v225
	ds_read_b128 v[98:101], v210 offset:49152
	v_exp_f32_e32 v249, v102
	v_add_f32_e32 v102, v247, v248
	s_waitcnt lgkmcnt(3)
	v_mfma_f32_32x32x16_bf16 v[82:97], v[240:243], v[138:141], v[82:97]
	ds_read_b128 v[210:213], v210 offset:57344
	v_add_f32_e32 v102, v249, v102
	v_exp_f32_e32 v248, v103
	s_waitcnt lgkmcnt(3)
	v_mfma_f32_32x32x16_bf16 v[114:129], v[186:189], v[142:145], v[114:129]
	v_add_u32_e32 v103, v220, v224
	ds_read_b128 v[236:239], v103 offset:49152
	v_add_f32_e32 v102, v248, v102
	v_exp_f32_e32 v240, v104
	s_waitcnt lgkmcnt(3)
	v_mfma_f32_32x32x16_bf16 v[82:97], v[190:193], v[142:145], v[82:97]
	ds_read_b128 v[186:189], v103 offset:57344
	v_add_f32_e32 v242, v240, v102
	v_exp_f32_e32 v241, v105
	s_waitcnt lgkmcnt(3)
	v_mfma_f32_32x32x16_bf16 v[114:129], v[98:101], v[154:157], v[114:129]
	v_add_u32_e32 v190, v220, v223
	ds_read_b128 v[102:105], v190 offset:49152
	v_add_f32_e32 v98, v241, v242
	v_exp_f32_e32 v243, v106
	s_waitcnt lgkmcnt(3)
	v_mfma_f32_32x32x16_bf16 v[82:97], v[210:213], v[154:157], v[82:97]
	ds_read_b128 v[190:193], v190 offset:57344
	v_add_f32_e32 v100, v243, v98
	v_exp_f32_e32 v242, v107
	v_cvt_pk_bf16_f32 v98, v244, v245
	v_cvt_pk_bf16_f32 v99, v246, v247
	s_waitcnt lgkmcnt(3)
	v_mfma_f32_32x32x16_bf16 v[114:129], v[236:239], v[150:153], v[114:129]
	v_add_u32_e32 v106, v220, v222
	ds_read_b128 v[210:213], v106 offset:49152
	v_add_f32_e32 v107, v242, v100
	v_exp_f32_e32 v220, v108
	v_cvt_pk_bf16_f32 v100, v249, v248
	v_cvt_pk_bf16_f32 v101, v240, v241
	s_waitcnt lgkmcnt(3)
	v_mfma_f32_32x32x16_bf16 v[82:97], v[186:189], v[150:153], v[82:97]
	ds_read_b128 v[236:239], v106 offset:57344
	v_add_f32_e32 v241, v220, v107
	v_permlane32_swap_b32_e32 v98, v100
	v_permlane32_swap_b32_e32 v99, v101
	v_exp_f32_e32 v240, v109
	s_waitcnt lgkmcnt(3)
	v_mfma_f32_32x32x16_bf16 v[114:129], v[102:105], v[146:149], v[114:129]
	v_add_u32_e32 v186, v234, v221
	ds_read_b128 v[106:109], v186
	v_exp_f32_e32 v244, v110
	v_add_f32_e32 v110, v240, v241
	s_waitcnt lgkmcnt(3)
	v_mfma_f32_32x32x16_bf16 v[82:97], v[190:193], v[146:149], v[82:97]
	ds_read_b128 v[102:105], v186 offset:4096
	v_add_f32_e32 v110, v244, v110
	v_exp_f32_e32 v241, v111
	s_waitcnt lgkmcnt(3)
	v_mfma_f32_32x32x16_bf16 v[114:129], v[210:213], v[158:161], v[114:129]
	v_add_u32_e32 v111, v234, v209
	ds_read_b128 v[186:189], v111
	v_add_f32_e32 v110, v241, v110
	v_exp_f32_e32 v245, v112
	s_waitcnt lgkmcnt(3)
	v_mfma_f32_32x32x16_bf16 v[82:97], v[236:239], v[158:161], v[82:97]
	ds_read_b128 v[190:193], v111 offset:4096
	v_add_f32_e32 v210, v245, v110
	v_exp_f32_e32 v246, v113
	s_waitcnt lgkmcnt(3)
	v_mfma_f32_32x32x16_bf16 v[114:129], v[106:109], v[162:165], v[114:129]
	v_add_u32_e32 v211, v234, v208
	ds_read_b128 v[110:113], v211
	v_add_f32_e32 v236, v246, v210
	s_waitcnt lgkmcnt(3)
	v_mfma_f32_32x32x16_bf16 v[82:97], v[102:105], v[162:165], v[82:97]
	ds_read_b128 v[106:109], v211 offset:4096
	v_cvt_pk_bf16_f32 v102, v243, v242
	v_cvt_pk_bf16_f32 v103, v220, v240
	s_waitcnt lgkmcnt(3)
	v_mfma_f32_32x32x16_bf16 v[114:129], v[186:189], v[166:169], v[114:129]
	v_add_u32_e32 v220, v234, v207
	ds_read_b128 v[210:213], v220
	v_cvt_pk_bf16_f32 v104, v244, v241
	v_cvt_pk_bf16_f32 v105, v245, v246
	s_waitcnt lgkmcnt(3)
	v_mfma_f32_32x32x16_bf16 v[82:97], v[190:193], v[166:169], v[82:97]
	ds_read_b128 v[186:189], v220 offset:4096
	v_permlane32_swap_b32_e32 v102, v104
	v_permlane32_swap_b32_e32 v103, v105
	s_waitcnt lgkmcnt(3)
	v_mfma_f32_32x32x16_bf16 v[114:129], v[110:113], v[170:173], v[114:129]
	v_mov_b32_e32 v110, v236
	s_nop 1
	v_permlane32_swap_b32_e32 v236, v110
	v_add_f32_e32 v110, v236, v110
	v_add_f32_e32 v234, v1, v110
	s_waitcnt lgkmcnt(2)
	v_mfma_f32_32x32x16_bf16 v[82:97], v[106:109], v[170:173], v[82:97]
	ds_read_b64_tr_b16 v[110:111], v235
	ds_read_b64_tr_b16 v[112:113], v235 offset:2048
	s_waitcnt lgkmcnt(3)
	v_mfma_f32_32x32x16_bf16 v[114:129], v[210:213], v[174:177], v[114:129]
	ds_read_b64_tr_b16 v[236:237], v235 offset:512
	ds_read_b64_tr_b16 v[238:239], v235 offset:2560
	s_waitcnt lgkmcnt(4)
	v_mfma_f32_32x32x16_bf16 v[82:97], v[186:189], v[174:177], v[82:97]
	ds_read_b64_tr_b16 v[106:107], v235 offset:1024
	ds_read_b64_tr_b16 v[108:109], v235 offset:3072
	s_waitcnt lgkmcnt(4)
	v_mfma_f32_32x32x16_bf16 v[50:65], v[182:185], v[110:113], v[50:65]
	s_cmpk_lt_u32 s78, 0x7c
	s_cselect_b64 s[6:7], -1, 0
	s_add_i32 s8, s13, s76
	ds_read_b64_tr_b16 v[190:191], v235 offset:1536
	ds_read_b64_tr_b16 v[192:193], v235 offset:3584
	s_add_u32 s12, s18, 0x15018100
	s_addc_u32 s13, s19, 0
	s_add_i32 s1, s1, s73
	s_mov_b32 m0, s1
	s_nop 0
	global_load_lds_dwordx4 v199, s[12:13]
	s_add_u32 s18, s18, 0x1501c100
	s_addc_u32 s19, s19, 0
	s_add_i32 s5, s1, 0x2000
	s_cmpk_gt_u32 s78, 0x7b
	s_waitcnt lgkmcnt(4)
	v_mfma_f32_32x32x16_bf16 v[34:49], v[182:185], v[236:239], v[34:49]
	ds_read_b64_tr_b16 v[186:187], v235 offset:4096
	ds_read_b64_tr_b16 v[188:189], v235 offset:6144
	s_mov_b32 m0, s5
	s_nop 0
	global_load_lds_dwordx4 v199, s[18:19]
	ds_read_b64_tr_b16 v[110:111], v235 offset:4608
	ds_read_b64_tr_b16 v[112:113], v235 offset:6656
	s_cbranch_scc1 .LBB0_246
	s_add_u32 s12, s14, 0x20000
	s_addc_u32 s13, s15, 0
	s_mov_b32 m0, s8
	s_nop 0
	global_load_lds_dwordx4 v197, s[12:13]
